# double-tile loops: counted lgkmcnt waits so the first 16 MFMAs start before the second row tile's fragments arrive
# baseline (speedup 1.0000x reference)
.Lg2_k:
	s_waitcnt vmcnt(0)
	s_barrier
	s_add_i32 m0, s58, 0xc000
	s_nop 0
	global_load_lds_dwordx4 v74, s[56:57]
	s_add_i32 m0, s58, 0xd000
	s_nop 0
	global_load_lds_dwordx4 v75, s[56:57]
	s_add_i32 m0, s58, 0xe000
	s_nop 0
	global_load_lds_dwordx4 v76, s[56:57]
	s_add_i32 m0, s58, 0xf000
	s_nop 0
	global_load_lds_dwordx4 v77, s[56:57]
	s_add_u32 s56, s56, 0x80
	s_addc_u32 s57, s57, 0
	ds_read_b128 v[148:151], v78 offset:0
	ds_read_b128 v[152:155], v78 offset:2048
	ds_read_b128 v[156:159], v78 offset:4096
	ds_read_b128 v[160:163], v78 offset:6144
	ds_read_b128 v[188:191], v79 offset:32768
	ds_read_b128 v[192:195], v79 offset:34816
	ds_read_b128 v[208:211], v79 offset:36864
	ds_read_b128 v[212:215], v79 offset:38912
	ds_read_b128 v[164:167], v78 offset:16384
	ds_read_b128 v[168:171], v78 offset:18432
	ds_read_b128 v[174:177], v78 offset:20480
	ds_read_b128 v[182:185], v78 offset:22528
	s_setprio 1
	s_waitcnt lgkmcnt(4)
	v_mfma_f32_16x16x32_bf16 v[62:65], v[188:191], v[148:151], v[62:65]
	v_mfma_f32_16x16x32_bf16 v[58:61], v[192:195], v[148:151], v[58:61]
	v_mfma_f32_16x16x32_bf16 v[54:57], v[208:211], v[148:151], v[54:57]
	v_mfma_f32_16x16x32_bf16 v[50:53], v[212:215], v[148:151], v[50:53]
	v_mfma_f32_16x16x32_bf16 v[46:49], v[188:191], v[152:155], v[46:49]
	v_mfma_f32_16x16x32_bf16 v[42:45], v[192:195], v[152:155], v[42:45]
	v_mfma_f32_16x16x32_bf16 v[38:41], v[208:211], v[152:155], v[38:41]
	v_mfma_f32_16x16x32_bf16 v[34:37], v[212:215], v[152:155], v[34:37]
	v_mfma_f32_16x16x32_bf16 v[30:33], v[188:191], v[156:159], v[30:33]
	v_mfma_f32_16x16x32_bf16 v[26:29], v[192:195], v[156:159], v[26:29]
	v_mfma_f32_16x16x32_bf16 v[22:25], v[208:211], v[156:159], v[22:25]
	v_mfma_f32_16x16x32_bf16 v[18:21], v[212:215], v[156:159], v[18:21]
	v_mfma_f32_16x16x32_bf16 v[14:17], v[188:191], v[160:163], v[14:17]
	v_mfma_f32_16x16x32_bf16 v[10:13], v[192:195], v[160:163], v[10:13]
	v_mfma_f32_16x16x32_bf16 v[6:9], v[208:211], v[160:163], v[6:9]
	v_mfma_f32_16x16x32_bf16 v[2:5], v[212:215], v[160:163], v[2:5]
	s_waitcnt lgkmcnt(0)
	v_mfma_f32_16x16x32_bf16 v[66:69], v[188:191], v[164:167], v[66:69]
	v_mfma_f32_16x16x32_bf16 v[70:73], v[192:195], v[164:167], v[70:73]
	v_mfma_f32_16x16x32_bf16 v[82:85], v[208:211], v[164:167], v[82:85]
	v_mfma_f32_16x16x32_bf16 v[88:91], v[212:215], v[164:167], v[88:91]
	v_mfma_f32_16x16x32_bf16 v[92:95], v[188:191], v[168:171], v[92:95]
	v_mfma_f32_16x16x32_bf16 v[96:99], v[192:195], v[168:171], v[96:99]
	v_mfma_f32_16x16x32_bf16 v[100:103], v[208:211], v[168:171], v[100:103]
	v_mfma_f32_16x16x32_bf16 v[106:109], v[212:215], v[168:171], v[106:109]
	v_mfma_f32_16x16x32_bf16 v[110:113], v[188:191], v[174:177], v[110:113]
	v_mfma_f32_16x16x32_bf16 v[114:117], v[192:195], v[174:177], v[114:117]
	v_mfma_f32_16x16x32_bf16 v[118:121], v[208:211], v[174:177], v[118:121]
	v_mfma_f32_16x16x32_bf16 v[122:125], v[212:215], v[174:177], v[122:125]
	v_mfma_f32_16x16x32_bf16 v[126:129], v[188:191], v[182:185], v[126:129]
	v_mfma_f32_16x16x32_bf16 v[136:139], v[192:195], v[182:185], v[136:139]
	v_mfma_f32_16x16x32_bf16 v[140:143], v[208:211], v[182:185], v[140:143]
	v_mfma_f32_16x16x32_bf16 v[144:147], v[212:215], v[182:185], v[144:147]
	s_setprio 0
	ds_read_b128 v[148:151], v80 offset:0
	ds_read_b128 v[152:155], v80 offset:2048
	ds_read_b128 v[156:159], v80 offset:4096
	ds_read_b128 v[160:163], v80 offset:6144
	ds_read_b128 v[188:191], v81 offset:32768
	ds_read_b128 v[192:195], v81 offset:34816
	ds_read_b128 v[208:211], v81 offset:36864
	ds_read_b128 v[212:215], v81 offset:38912
	ds_read_b128 v[164:167], v80 offset:16384
	ds_read_b128 v[168:171], v80 offset:18432
	ds_read_b128 v[174:177], v80 offset:20480
	ds_read_b128 v[182:185], v80 offset:22528
	s_waitcnt lgkmcnt(0)
	s_barrier
	s_add_i32 m0, s58, 0x0
	s_nop 0
	global_load_lds_dwordx4 v74, s[50:51]
	s_add_i32 m0, s58, 0x1000
	s_nop 0
	global_load_lds_dwordx4 v75, s[50:51]
	s_add_i32 m0, s58, 0x2000
	s_nop 0
	global_load_lds_dwordx4 v76, s[50:51]
	s_add_i32 m0, s58, 0x3000
	s_nop 0
	global_load_lds_dwordx4 v77, s[50:51]
	s_add_i32 m0, s58, 0x4000
	s_nop 0
	global_load_lds_dwordx4 v74, s[52:53]
	s_add_i32 m0, s58, 0x5000
	s_nop 0
	global_load_lds_dwordx4 v75, s[52:53]
	s_add_i32 m0, s58, 0x6000
	s_nop 0
	global_load_lds_dwordx4 v76, s[52:53]
	s_add_i32 m0, s58, 0x7000
	s_nop 0
	global_load_lds_dwordx4 v77, s[52:53]
	s_add_u32 s50, s50, 0x80
	s_addc_u32 s51, s51, 0
	s_add_u32 s52, s52, 0x80
	s_addc_u32 s53, s53, 0
	s_setprio 1
	v_mfma_f32_16x16x32_bf16 v[62:65], v[188:191], v[148:151], v[62:65]
	v_mfma_f32_16x16x32_bf16 v[58:61], v[192:195], v[148:151], v[58:61]
	v_mfma_f32_16x16x32_bf16 v[54:57], v[208:211], v[148:151], v[54:57]
	v_mfma_f32_16x16x32_bf16 v[50:53], v[212:215], v[148:151], v[50:53]
	v_mfma_f32_16x16x32_bf16 v[46:49], v[188:191], v[152:155], v[46:49]
	v_mfma_f32_16x16x32_bf16 v[42:45], v[192:195], v[152:155], v[42:45]
	v_mfma_f32_16x16x32_bf16 v[38:41], v[208:211], v[152:155], v[38:41]
	v_mfma_f32_16x16x32_bf16 v[34:37], v[212:215], v[152:155], v[34:37]
	v_mfma_f32_16x16x32_bf16 v[30:33], v[188:191], v[156:159], v[30:33]
	v_mfma_f32_16x16x32_bf16 v[26:29], v[192:195], v[156:159], v[26:29]
	v_mfma_f32_16x16x32_bf16 v[22:25], v[208:211], v[156:159], v[22:25]
	v_mfma_f32_16x16x32_bf16 v[18:21], v[212:215], v[156:159], v[18:21]
	v_mfma_f32_16x16x32_bf16 v[14:17], v[188:191], v[160:163], v[14:17]
	v_mfma_f32_16x16x32_bf16 v[10:13], v[192:195], v[160:163], v[10:13]
	v_mfma_f32_16x16x32_bf16 v[6:9], v[208:211], v[160:163], v[6:9]
	v_mfma_f32_16x16x32_bf16 v[2:5], v[212:215], v[160:163], v[2:5]
	v_mfma_f32_16x16x32_bf16 v[66:69], v[188:191], v[164:167], v[66:69]
	v_mfma_f32_16x16x32_bf16 v[70:73], v[192:195], v[164:167], v[70:73]
	v_mfma_f32_16x16x32_bf16 v[82:85], v[208:211], v[164:167], v[82:85]
	v_mfma_f32_16x16x32_bf16 v[88:91], v[212:215], v[164:167], v[88:91]
	v_mfma_f32_16x16x32_bf16 v[92:95], v[188:191], v[168:171], v[92:95]
	v_mfma_f32_16x16x32_bf16 v[96:99], v[192:195], v[168:171], v[96:99]
	v_mfma_f32_16x16x32_bf16 v[100:103], v[208:211], v[168:171], v[100:103]
	v_mfma_f32_16x16x32_bf16 v[106:109], v[212:215], v[168:171], v[106:109]
	v_mfma_f32_16x16x32_bf16 v[110:113], v[188:191], v[174:177], v[110:113]
	v_mfma_f32_16x16x32_bf16 v[114:117], v[192:195], v[174:177], v[114:117]
	v_mfma_f32_16x16x32_bf16 v[118:121], v[208:211], v[174:177], v[118:121]
	v_mfma_f32_16x16x32_bf16 v[122:125], v[212:215], v[174:177], v[122:125]
	v_mfma_f32_16x16x32_bf16 v[126:129], v[188:191], v[182:185], v[126:129]
	v_mfma_f32_16x16x32_bf16 v[136:139], v[192:195], v[182:185], v[136:139]
	v_mfma_f32_16x16x32_bf16 v[140:143], v[208:211], v[182:185], v[140:143]
	v_mfma_f32_16x16x32_bf16 v[144:147], v[212:215], v[182:185], v[144:147]
	s_setprio 0
	s_waitcnt vmcnt(0)
	s_barrier
	s_add_i32 m0, s58, 0x8000
	s_nop 0
	global_load_lds_dwordx4 v74, s[56:57]
	s_add_i32 m0, s58, 0x9000
	s_nop 0
	global_load_lds_dwordx4 v75, s[56:57]
	s_add_i32 m0, s58, 0xa000
	s_nop 0
	global_load_lds_dwordx4 v76, s[56:57]
	s_add_i32 m0, s58, 0xb000
	s_nop 0
	global_load_lds_dwordx4 v77, s[56:57]
	s_add_u32 s56, s56, 0x80
	s_addc_u32 s57, s57, 0
	ds_read_b128 v[148:151], v78 offset:0
	ds_read_b128 v[152:155], v78 offset:2048
	ds_read_b128 v[156:159], v78 offset:4096
	ds_read_b128 v[160:163], v78 offset:6144
	ds_read_b128 v[188:191], v79 offset:49152
	ds_read_b128 v[192:195], v79 offset:51200
	ds_read_b128 v[208:211], v79 offset:53248
	ds_read_b128 v[212:215], v79 offset:55296
	ds_read_b128 v[164:167], v78 offset:16384
	ds_read_b128 v[168:171], v78 offset:18432
	ds_read_b128 v[174:177], v78 offset:20480
	ds_read_b128 v[182:185], v78 offset:22528
	s_setprio 1
	s_waitcnt lgkmcnt(4)
	v_mfma_f32_16x16x32_bf16 v[62:65], v[188:191], v[148:151], v[62:65]
	v_mfma_f32_16x16x32_bf16 v[58:61], v[192:195], v[148:151], v[58:61]
	v_mfma_f32_16x16x32_bf16 v[54:57], v[208:211], v[148:151], v[54:57]
	v_mfma_f32_16x16x32_bf16 v[50:53], v[212:215], v[148:151], v[50:53]
	v_mfma_f32_16x16x32_bf16 v[46:49], v[188:191], v[152:155], v[46:49]
	v_mfma_f32_16x16x32_bf16 v[42:45], v[192:195], v[152:155], v[42:45]
	v_mfma_f32_16x16x32_bf16 v[38:41], v[208:211], v[152:155], v[38:41]
	v_mfma_f32_16x16x32_bf16 v[34:37], v[212:215], v[152:155], v[34:37]
	v_mfma_f32_16x16x32_bf16 v[30:33], v[188:191], v[156:159], v[30:33]
	v_mfma_f32_16x16x32_bf16 v[26:29], v[192:195], v[156:159], v[26:29]
	v_mfma_f32_16x16x32_bf16 v[22:25], v[208:211], v[156:159], v[22:25]
	v_mfma_f32_16x16x32_bf16 v[18:21], v[212:215], v[156:159], v[18:21]
	v_mfma_f32_16x16x32_bf16 v[14:17], v[188:191], v[160:163], v[14:17]
	v_mfma_f32_16x16x32_bf16 v[10:13], v[192:195], v[160:163], v[10:13]
	v_mfma_f32_16x16x32_bf16 v[6:9], v[208:211], v[160:163], v[6:9]
	v_mfma_f32_16x16x32_bf16 v[2:5], v[212:215], v[160:163], v[2:5]
	s_waitcnt lgkmcnt(0)
	v_mfma_f32_16x16x32_bf16 v[66:69], v[188:191], v[164:167], v[66:69]
	v_mfma_f32_16x16x32_bf16 v[70:73], v[192:195], v[164:167], v[70:73]
	v_mfma_f32_16x16x32_bf16 v[82:85], v[208:211], v[164:167], v[82:85]
	v_mfma_f32_16x16x32_bf16 v[88:91], v[212:215], v[164:167], v[88:91]
	v_mfma_f32_16x16x32_bf16 v[92:95], v[188:191], v[168:171], v[92:95]
	v_mfma_f32_16x16x32_bf16 v[96:99], v[192:195], v[168:171], v[96:99]
	v_mfma_f32_16x16x32_bf16 v[100:103], v[208:211], v[168:171], v[100:103]
	v_mfma_f32_16x16x32_bf16 v[106:109], v[212:215], v[168:171], v[106:109]
	v_mfma_f32_16x16x32_bf16 v[110:113], v[188:191], v[174:177], v[110:113]
	v_mfma_f32_16x16x32_bf16 v[114:117], v[192:195], v[174:177], v[114:117]
	v_mfma_f32_16x16x32_bf16 v[118:121], v[208:211], v[174:177], v[118:121]
	v_mfma_f32_16x16x32_bf16 v[122:125], v[212:215], v[174:177], v[122:125]
	v_mfma_f32_16x16x32_bf16 v[126:129], v[188:191], v[182:185], v[126:129]
	v_mfma_f32_16x16x32_bf16 v[136:139], v[192:195], v[182:185], v[136:139]
	v_mfma_f32_16x16x32_bf16 v[140:143], v[208:211], v[182:185], v[140:143]
	v_mfma_f32_16x16x32_bf16 v[144:147], v[212:215], v[182:185], v[144:147]
	s_setprio 0
	ds_read_b128 v[148:151], v80 offset:0
	ds_read_b128 v[152:155], v80 offset:2048
	ds_read_b128 v[156:159], v80 offset:4096
	ds_read_b128 v[160:163], v80 offset:6144
	ds_read_b128 v[188:191], v81 offset:49152
	ds_read_b128 v[192:195], v81 offset:51200
	ds_read_b128 v[208:211], v81 offset:53248
	ds_read_b128 v[212:215], v81 offset:55296
	ds_read_b128 v[164:167], v80 offset:16384
	ds_read_b128 v[168:171], v80 offset:18432
	ds_read_b128 v[174:177], v80 offset:20480
	ds_read_b128 v[182:185], v80 offset:22528
	s_waitcnt lgkmcnt(0)
	s_barrier
	s_add_i32 m0, s58, 0x0
	s_nop 0
	global_load_lds_dwordx4 v74, s[50:51]
	s_add_i32 m0, s58, 0x1000
	s_nop 0
	global_load_lds_dwordx4 v75, s[50:51]
	s_add_i32 m0, s58, 0x2000
	s_nop 0
	global_load_lds_dwordx4 v76, s[50:51]
	s_add_i32 m0, s58, 0x3000
	s_nop 0
	global_load_lds_dwordx4 v77, s[50:51]
	s_add_i32 m0, s58, 0x4000
	s_nop 0
	global_load_lds_dwordx4 v74, s[52:53]
	s_add_i32 m0, s58, 0x5000
	s_nop 0
	global_load_lds_dwordx4 v75, s[52:53]
	s_add_i32 m0, s58, 0x6000
	s_nop 0
	global_load_lds_dwordx4 v76, s[52:53]
	s_add_i32 m0, s58, 0x7000
	s_nop 0
	global_load_lds_dwordx4 v77, s[52:53]
	s_add_u32 s50, s50, 0x80
	s_addc_u32 s51, s51, 0
	s_add_u32 s52, s52, 0x80
	s_addc_u32 s53, s53, 0
	s_setprio 1
	v_mfma_f32_16x16x32_bf16 v[62:65], v[188:191], v[148:151], v[62:65]
	v_mfma_f32_16x16x32_bf16 v[58:61], v[192:195], v[148:151], v[58:61]
	v_mfma_f32_16x16x32_bf16 v[54:57], v[208:211], v[148:151], v[54:57]
	v_mfma_f32_16x16x32_bf16 v[50:53], v[212:215], v[148:151], v[50:53]
	v_mfma_f32_16x16x32_bf16 v[46:49], v[188:191], v[152:155], v[46:49]
	v_mfma_f32_16x16x32_bf16 v[42:45], v[192:195], v[152:155], v[42:45]
	v_mfma_f32_16x16x32_bf16 v[38:41], v[208:211], v[152:155], v[38:41]
	v_mfma_f32_16x16x32_bf16 v[34:37], v[212:215], v[152:155], v[34:37]
	v_mfma_f32_16x16x32_bf16 v[30:33], v[188:191], v[156:159], v[30:33]
	v_mfma_f32_16x16x32_bf16 v[26:29], v[192:195], v[156:159], v[26:29]
	v_mfma_f32_16x16x32_bf16 v[22:25], v[208:211], v[156:159], v[22:25]
	v_mfma_f32_16x16x32_bf16 v[18:21], v[212:215], v[156:159], v[18:21]
	v_mfma_f32_16x16x32_bf16 v[14:17], v[188:191], v[160:163], v[14:17]
	v_mfma_f32_16x16x32_bf16 v[10:13], v[192:195], v[160:163], v[10:13]
	v_mfma_f32_16x16x32_bf16 v[6:9], v[208:211], v[160:163], v[6:9]
	v_mfma_f32_16x16x32_bf16 v[2:5], v[212:215], v[160:163], v[2:5]
	v_mfma_f32_16x16x32_bf16 v[66:69], v[188:191], v[164:167], v[66:69]
	v_mfma_f32_16x16x32_bf16 v[70:73], v[192:195], v[164:167], v[70:73]
	v_mfma_f32_16x16x32_bf16 v[82:85], v[208:211], v[164:167], v[82:85]
	v_mfma_f32_16x16x32_bf16 v[88:91], v[212:215], v[164:167], v[88:91]
	v_mfma_f32_16x16x32_bf16 v[92:95], v[188:191], v[168:171], v[92:95]
	v_mfma_f32_16x16x32_bf16 v[96:99], v[192:195], v[168:171], v[96:99]
	v_mfma_f32_16x16x32_bf16 v[100:103], v[208:211], v[168:171], v[100:103]
	v_mfma_f32_16x16x32_bf16 v[106:109], v[212:215], v[168:171], v[106:109]
	v_mfma_f32_16x16x32_bf16 v[110:113], v[188:191], v[174:177], v[110:113]
	v_mfma_f32_16x16x32_bf16 v[114:117], v[192:195], v[174:177], v[114:117]
	v_mfma_f32_16x16x32_bf16 v[118:121], v[208:211], v[174:177], v[118:121]
	v_mfma_f32_16x16x32_bf16 v[122:125], v[212:215], v[174:177], v[122:125]
	v_mfma_f32_16x16x32_bf16 v[126:129], v[188:191], v[182:185], v[126:129]
	v_mfma_f32_16x16x32_bf16 v[136:139], v[192:195], v[182:185], v[136:139]
	v_mfma_f32_16x16x32_bf16 v[140:143], v[208:211], v[182:185], v[140:143]
	v_mfma_f32_16x16x32_bf16 v[144:147], v[212:215], v[182:185], v[144:147]
	s_setprio 0
	s_add_i32 s59, s59, -1
	s_cmp_lg_u32 s59, 0
	s_cbranch_scc1 .Lg2_k
	s_waitcnt vmcnt(0)
	s_barrier
	s_add_i32 m0, s58, 0xc000
	s_nop 0
	global_load_lds_dwordx4 v74, s[56:57]
	s_add_i32 m0, s58, 0xd000
	s_nop 0
	global_load_lds_dwordx4 v75, s[56:57]
	s_add_i32 m0, s58, 0xe000
	s_nop 0
	global_load_lds_dwordx4 v76, s[56:57]
	s_add_i32 m0, s58, 0xf000
	s_nop 0
	global_load_lds_dwordx4 v77, s[56:57]
	s_add_u32 s56, s56, 0x80
	s_addc_u32 s57, s57, 0
	ds_read_b128 v[148:151], v78 offset:0
	ds_read_b128 v[152:155], v78 offset:2048
	ds_read_b128 v[156:159], v78 offset:4096
	ds_read_b128 v[160:163], v78 offset:6144
	ds_read_b128 v[188:191], v79 offset:32768
	ds_read_b128 v[192:195], v79 offset:34816
	ds_read_b128 v[208:211], v79 offset:36864
	ds_read_b128 v[212:215], v79 offset:38912
	ds_read_b128 v[164:167], v78 offset:16384
	ds_read_b128 v[168:171], v78 offset:18432
	ds_read_b128 v[174:177], v78 offset:20480
	ds_read_b128 v[182:185], v78 offset:22528
	s_setprio 1
	s_waitcnt lgkmcnt(4)
	v_mfma_f32_16x16x32_bf16 v[62:65], v[188:191], v[148:151], v[62:65]
	v_mfma_f32_16x16x32_bf16 v[58:61], v[192:195], v[148:151], v[58:61]
	v_mfma_f32_16x16x32_bf16 v[54:57], v[208:211], v[148:151], v[54:57]
	v_mfma_f32_16x16x32_bf16 v[50:53], v[212:215], v[148:151], v[50:53]
	v_mfma_f32_16x16x32_bf16 v[46:49], v[188:191], v[152:155], v[46:49]
	v_mfma_f32_16x16x32_bf16 v[42:45], v[192:195], v[152:155], v[42:45]
	v_mfma_f32_16x16x32_bf16 v[38:41], v[208:211], v[152:155], v[38:41]
	v_mfma_f32_16x16x32_bf16 v[34:37], v[212:215], v[152:155], v[34:37]
	v_mfma_f32_16x16x32_bf16 v[30:33], v[188:191], v[156:159], v[30:33]
	v_mfma_f32_16x16x32_bf16 v[26:29], v[192:195], v[156:159], v[26:29]
	v_mfma_f32_16x16x32_bf16 v[22:25], v[208:211], v[156:159], v[22:25]
	v_mfma_f32_16x16x32_bf16 v[18:21], v[212:215], v[156:159], v[18:21]
	v_mfma_f32_16x16x32_bf16 v[14:17], v[188:191], v[160:163], v[14:17]
	v_mfma_f32_16x16x32_bf16 v[10:13], v[192:195], v[160:163], v[10:13]
	v_mfma_f32_16x16x32_bf16 v[6:9], v[208:211], v[160:163], v[6:9]
	v_mfma_f32_16x16x32_bf16 v[2:5], v[212:215], v[160:163], v[2:5]
	s_waitcnt lgkmcnt(0)
	v_mfma_f32_16x16x32_bf16 v[66:69], v[188:191], v[164:167], v[66:69]
	v_mfma_f32_16x16x32_bf16 v[70:73], v[192:195], v[164:167], v[70:73]
	v_mfma_f32_16x16x32_bf16 v[82:85], v[208:211], v[164:167], v[82:85]
	v_mfma_f32_16x16x32_bf16 v[88:91], v[212:215], v[164:167], v[88:91]
	v_mfma_f32_16x16x32_bf16 v[92:95], v[188:191], v[168:171], v[92:95]
	v_mfma_f32_16x16x32_bf16 v[96:99], v[192:195], v[168:171], v[96:99]
	v_mfma_f32_16x16x32_bf16 v[100:103], v[208:211], v[168:171], v[100:103]
	v_mfma_f32_16x16x32_bf16 v[106:109], v[212:215], v[168:171], v[106:109]
	v_mfma_f32_16x16x32_bf16 v[110:113], v[188:191], v[174:177], v[110:113]
	v_mfma_f32_16x16x32_bf16 v[114:117], v[192:195], v[174:177], v[114:117]
	v_mfma_f32_16x16x32_bf16 v[118:121], v[208:211], v[174:177], v[118:121]
	v_mfma_f32_16x16x32_bf16 v[122:125], v[212:215], v[174:177], v[122:125]
	v_mfma_f32_16x16x32_bf16 v[126:129], v[188:191], v[182:185], v[126:129]
	v_mfma_f32_16x16x32_bf16 v[136:139], v[192:195], v[182:185], v[136:139]
	v_mfma_f32_16x16x32_bf16 v[140:143], v[208:211], v[182:185], v[140:143]
	v_mfma_f32_16x16x32_bf16 v[144:147], v[212:215], v[182:185], v[144:147]
	s_setprio 0
	ds_read_b128 v[148:151], v80 offset:0
	ds_read_b128 v[152:155], v80 offset:2048
	ds_read_b128 v[156:159], v80 offset:4096
	ds_read_b128 v[160:163], v80 offset:6144
	ds_read_b128 v[188:191], v81 offset:32768
	ds_read_b128 v[192:195], v81 offset:34816
	ds_read_b128 v[208:211], v81 offset:36864
	ds_read_b128 v[212:215], v81 offset:38912
	ds_read_b128 v[164:167], v80 offset:16384
	ds_read_b128 v[168:171], v80 offset:18432
	ds_read_b128 v[174:177], v80 offset:20480
	ds_read_b128 v[182:185], v80 offset:22528
	s_waitcnt lgkmcnt(0)
	s_barrier
	s_add_i32 m0, s58, 0x0
	s_nop 0
	global_load_lds_dwordx4 v74, s[50:51]
	s_add_i32 m0, s58, 0x1000
	s_nop 0
	global_load_lds_dwordx4 v75, s[50:51]
	s_add_i32 m0, s58, 0x2000
	s_nop 0
	global_load_lds_dwordx4 v76, s[50:51]
	s_add_i32 m0, s58, 0x3000
	s_nop 0
	global_load_lds_dwordx4 v77, s[50:51]
	s_add_i32 m0, s58, 0x4000
	s_nop 0
	global_load_lds_dwordx4 v74, s[52:53]
	s_add_i32 m0, s58, 0x5000
	s_nop 0
	global_load_lds_dwordx4 v75, s[52:53]
	s_add_i32 m0, s58, 0x6000
	s_nop 0
	global_load_lds_dwordx4 v76, s[52:53]
	s_add_i32 m0, s58, 0x7000
	s_nop 0
	global_load_lds_dwordx4 v77, s[52:53]
	s_add_u32 s50, s50, 0x80
	s_addc_u32 s51, s51, 0
	s_add_u32 s52, s52, 0x80
	s_addc_u32 s53, s53, 0
	s_setprio 1
	v_mfma_f32_16x16x32_bf16 v[62:65], v[188:191], v[148:151], v[62:65]
	v_mfma_f32_16x16x32_bf16 v[58:61], v[192:195], v[148:151], v[58:61]
	v_mfma_f32_16x16x32_bf16 v[54:57], v[208:211], v[148:151], v[54:57]
	v_mfma_f32_16x16x32_bf16 v[50:53], v[212:215], v[148:151], v[50:53]
	v_mfma_f32_16x16x32_bf16 v[46:49], v[188:191], v[152:155], v[46:49]
	v_mfma_f32_16x16x32_bf16 v[42:45], v[192:195], v[152:155], v[42:45]
	v_mfma_f32_16x16x32_bf16 v[38:41], v[208:211], v[152:155], v[38:41]
	v_mfma_f32_16x16x32_bf16 v[34:37], v[212:215], v[152:155], v[34:37]
	v_mfma_f32_16x16x32_bf16 v[30:33], v[188:191], v[156:159], v[30:33]
	v_mfma_f32_16x16x32_bf16 v[26:29], v[192:195], v[156:159], v[26:29]
	v_mfma_f32_16x16x32_bf16 v[22:25], v[208:211], v[156:159], v[22:25]
	v_mfma_f32_16x16x32_bf16 v[18:21], v[212:215], v[156:159], v[18:21]
	v_mfma_f32_16x16x32_bf16 v[14:17], v[188:191], v[160:163], v[14:17]
	v_mfma_f32_16x16x32_bf16 v[10:13], v[192:195], v[160:163], v[10:13]
	v_mfma_f32_16x16x32_bf16 v[6:9], v[208:211], v[160:163], v[6:9]
	v_mfma_f32_16x16x32_bf16 v[2:5], v[212:215], v[160:163], v[2:5]
	v_mfma_f32_16x16x32_bf16 v[66:69], v[188:191], v[164:167], v[66:69]
	v_mfma_f32_16x16x32_bf16 v[70:73], v[192:195], v[164:167], v[70:73]
	v_mfma_f32_16x16x32_bf16 v[82:85], v[208:211], v[164:167], v[82:85]
	v_mfma_f32_16x16x32_bf16 v[88:91], v[212:215], v[164:167], v[88:91]
	v_mfma_f32_16x16x32_bf16 v[92:95], v[188:191], v[168:171], v[92:95]
	v_mfma_f32_16x16x32_bf16 v[96:99], v[192:195], v[168:171], v[96:99]
	v_mfma_f32_16x16x32_bf16 v[100:103], v[208:211], v[168:171], v[100:103]
	v_mfma_f32_16x16x32_bf16 v[106:109], v[212:215], v[168:171], v[106:109]
	v_mfma_f32_16x16x32_bf16 v[110:113], v[188:191], v[174:177], v[110:113]
	v_mfma_f32_16x16x32_bf16 v[114:117], v[192:195], v[174:177], v[114:117]
	v_mfma_f32_16x16x32_bf16 v[118:121], v[208:211], v[174:177], v[118:121]
	v_mfma_f32_16x16x32_bf16 v[122:125], v[212:215], v[174:177], v[122:125]
	v_mfma_f32_16x16x32_bf16 v[126:129], v[188:191], v[182:185], v[126:129]
	v_mfma_f32_16x16x32_bf16 v[136:139], v[192:195], v[182:185], v[136:139]
	v_mfma_f32_16x16x32_bf16 v[140:143], v[208:211], v[182:185], v[140:143]
	v_mfma_f32_16x16x32_bf16 v[144:147], v[212:215], v[182:185], v[144:147]
	s_setprio 0
	s_waitcnt vmcnt(0)
	s_barrier
	ds_read_b128 v[148:151], v78 offset:0
	ds_read_b128 v[152:155], v78 offset:2048
	ds_read_b128 v[156:159], v78 offset:4096
	ds_read_b128 v[160:163], v78 offset:6144
	ds_read_b128 v[188:191], v79 offset:49152
	ds_read_b128 v[192:195], v79 offset:51200
	ds_read_b128 v[208:211], v79 offset:53248
	ds_read_b128 v[212:215], v79 offset:55296
	ds_read_b128 v[164:167], v78 offset:16384
	ds_read_b128 v[168:171], v78 offset:18432
	ds_read_b128 v[174:177], v78 offset:20480
	ds_read_b128 v[182:185], v78 offset:22528
	s_setprio 1
	s_waitcnt lgkmcnt(4)
	v_mfma_f32_16x16x32_bf16 v[62:65], v[188:191], v[148:151], v[62:65]
	v_mfma_f32_16x16x32_bf16 v[58:61], v[192:195], v[148:151], v[58:61]
	v_mfma_f32_16x16x32_bf16 v[54:57], v[208:211], v[148:151], v[54:57]
	v_mfma_f32_16x16x32_bf16 v[50:53], v[212:215], v[148:151], v[50:53]
	v_mfma_f32_16x16x32_bf16 v[46:49], v[188:191], v[152:155], v[46:49]
	v_mfma_f32_16x16x32_bf16 v[42:45], v[192:195], v[152:155], v[42:45]
	v_mfma_f32_16x16x32_bf16 v[38:41], v[208:211], v[152:155], v[38:41]
	v_mfma_f32_16x16x32_bf16 v[34:37], v[212:215], v[152:155], v[34:37]
	v_mfma_f32_16x16x32_bf16 v[30:33], v[188:191], v[156:159], v[30:33]
	v_mfma_f32_16x16x32_bf16 v[26:29], v[192:195], v[156:159], v[26:29]
	v_mfma_f32_16x16x32_bf16 v[22:25], v[208:211], v[156:159], v[22:25]
	v_mfma_f32_16x16x32_bf16 v[18:21], v[212:215], v[156:159], v[18:21]
	v_mfma_f32_16x16x32_bf16 v[14:17], v[188:191], v[160:163], v[14:17]
	v_mfma_f32_16x16x32_bf16 v[10:13], v[192:195], v[160:163], v[10:13]
	v_mfma_f32_16x16x32_bf16 v[6:9], v[208:211], v[160:163], v[6:9]
	v_mfma_f32_16x16x32_bf16 v[2:5], v[212:215], v[160:163], v[2:5]
	s_waitcnt lgkmcnt(0)
	v_mfma_f32_16x16x32_bf16 v[66:69], v[188:191], v[164:167], v[66:69]
	v_mfma_f32_16x16x32_bf16 v[70:73], v[192:195], v[164:167], v[70:73]
	v_mfma_f32_16x16x32_bf16 v[82:85], v[208:211], v[164:167], v[82:85]
	v_mfma_f32_16x16x32_bf16 v[88:91], v[212:215], v[164:167], v[88:91]
	v_mfma_f32_16x16x32_bf16 v[92:95], v[188:191], v[168:171], v[92:95]
	v_mfma_f32_16x16x32_bf16 v[96:99], v[192:195], v[168:171], v[96:99]
	v_mfma_f32_16x16x32_bf16 v[100:103], v[208:211], v[168:171], v[100:103]
	v_mfma_f32_16x16x32_bf16 v[106:109], v[212:215], v[168:171], v[106:109]
	v_mfma_f32_16x16x32_bf16 v[110:113], v[188:191], v[174:177], v[110:113]
	v_mfma_f32_16x16x32_bf16 v[114:117], v[192:195], v[174:177], v[114:117]
	v_mfma_f32_16x16x32_bf16 v[118:121], v[208:211], v[174:177], v[118:121]
	v_mfma_f32_16x16x32_bf16 v[122:125], v[212:215], v[174:177], v[122:125]
	v_mfma_f32_16x16x32_bf16 v[126:129], v[188:191], v[182:185], v[126:129]
	v_mfma_f32_16x16x32_bf16 v[136:139], v[192:195], v[182:185], v[136:139]
	v_mfma_f32_16x16x32_bf16 v[140:143], v[208:211], v[182:185], v[140:143]
	v_mfma_f32_16x16x32_bf16 v[144:147], v[212:215], v[182:185], v[144:147]
	s_setprio 0
	ds_read_b128 v[148:151], v80 offset:0
	ds_read_b128 v[152:155], v80 offset:2048
	ds_read_b128 v[156:159], v80 offset:4096
	ds_read_b128 v[160:163], v80 offset:6144
	ds_read_b128 v[188:191], v81 offset:49152
	ds_read_b128 v[192:195], v81 offset:51200
	ds_read_b128 v[208:211], v81 offset:53248
	ds_read_b128 v[212:215], v81 offset:55296
	ds_read_b128 v[164:167], v80 offset:16384
	ds_read_b128 v[168:171], v80 offset:18432
	ds_read_b128 v[174:177], v80 offset:20480
	ds_read_b128 v[182:185], v80 offset:22528
	s_setprio 1
	s_waitcnt lgkmcnt(4)
	v_mfma_f32_16x16x32_bf16 v[62:65], v[188:191], v[148:151], v[62:65]
	v_mfma_f32_16x16x32_bf16 v[58:61], v[192:195], v[148:151], v[58:61]
	v_mfma_f32_16x16x32_bf16 v[54:57], v[208:211], v[148:151], v[54:57]
	v_mfma_f32_16x16x32_bf16 v[50:53], v[212:215], v[148:151], v[50:53]
	v_mfma_f32_16x16x32_bf16 v[46:49], v[188:191], v[152:155], v[46:49]
	v_mfma_f32_16x16x32_bf16 v[42:45], v[192:195], v[152:155], v[42:45]
	v_mfma_f32_16x16x32_bf16 v[38:41], v[208:211], v[152:155], v[38:41]
	v_mfma_f32_16x16x32_bf16 v[34:37], v[212:215], v[152:155], v[34:37]
	v_mfma_f32_16x16x32_bf16 v[30:33], v[188:191], v[156:159], v[30:33]
	v_mfma_f32_16x16x32_bf16 v[26:29], v[192:195], v[156:159], v[26:29]
	v_mfma_f32_16x16x32_bf16 v[22:25], v[208:211], v[156:159], v[22:25]
	v_mfma_f32_16x16x32_bf16 v[18:21], v[212:215], v[156:159], v[18:21]
	v_mfma_f32_16x16x32_bf16 v[14:17], v[188:191], v[160:163], v[14:17]
	v_mfma_f32_16x16x32_bf16 v[10:13], v[192:195], v[160:163], v[10:13]
	v_mfma_f32_16x16x32_bf16 v[6:9], v[208:211], v[160:163], v[6:9]
	v_mfma_f32_16x16x32_bf16 v[2:5], v[212:215], v[160:163], v[2:5]
	s_waitcnt lgkmcnt(0)
	v_mfma_f32_16x16x32_bf16 v[66:69], v[188:191], v[164:167], v[66:69]
	v_mfma_f32_16x16x32_bf16 v[70:73], v[192:195], v[164:167], v[70:73]
	v_mfma_f32_16x16x32_bf16 v[82:85], v[208:211], v[164:167], v[82:85]
	v_mfma_f32_16x16x32_bf16 v[88:91], v[212:215], v[164:167], v[88:91]
	v_mfma_f32_16x16x32_bf16 v[92:95], v[188:191], v[168:171], v[92:95]
	v_mfma_f32_16x16x32_bf16 v[96:99], v[192:195], v[168:171], v[96:99]
	v_mfma_f32_16x16x32_bf16 v[100:103], v[208:211], v[168:171], v[100:103]
	v_mfma_f32_16x16x32_bf16 v[106:109], v[212:215], v[168:171], v[106:109]
	v_mfma_f32_16x16x32_bf16 v[110:113], v[188:191], v[174:177], v[110:113]
	v_mfma_f32_16x16x32_bf16 v[114:117], v[192:195], v[174:177], v[114:117]
	v_mfma_f32_16x16x32_bf16 v[118:121], v[208:211], v[174:177], v[118:121]
	v_mfma_f32_16x16x32_bf16 v[122:125], v[212:215], v[174:177], v[122:125]
	v_mfma_f32_16x16x32_bf16 v[126:129], v[188:191], v[182:185], v[126:129]
	v_mfma_f32_16x16x32_bf16 v[136:139], v[192:195], v[182:185], v[136:139]
	v_mfma_f32_16x16x32_bf16 v[140:143], v[208:211], v[182:185], v[140:143]
	v_mfma_f32_16x16x32_bf16 v[144:147], v[212:215], v[182:185], v[144:147]
	s_setprio 0
	s_nop 7
	s_nop 7
	s_nop 7
	v_mov_b32_e32 v148, v66
	v_mov_b32_e32 v149, v67
	v_mov_b32_e32 v150, v68
	v_mov_b32_e32 v151, v69
	v_mov_b32_e32 v152, v70
	v_mov_b32_e32 v153, v71
	v_mov_b32_e32 v154, v72
	v_mov_b32_e32 v155, v73
	v_mov_b32_e32 v156, v82
	v_mov_b32_e32 v157, v83
	v_mov_b32_e32 v158, v84
	v_mov_b32_e32 v159, v85
	v_mov_b32_e32 v160, v88
	v_mov_b32_e32 v161, v89
	v_mov_b32_e32 v162, v90
	v_mov_b32_e32 v163, v91
	v_mov_b32_e32 v164, v92
	v_mov_b32_e32 v165, v93
	v_mov_b32_e32 v166, v94
	v_mov_b32_e32 v167, v95
	v_mov_b32_e32 v168, v96
	v_mov_b32_e32 v169, v97
	v_mov_b32_e32 v170, v98
	v_mov_b32_e32 v171, v99
	v_mov_b32_e32 v174, v100
	v_mov_b32_e32 v175, v101
	v_mov_b32_e32 v176, v102
	v_mov_b32_e32 v177, v103
	v_mov_b32_e32 v182, v106
	v_mov_b32_e32 v183, v107
	v_mov_b32_e32 v184, v108
	v_mov_b32_e32 v185, v109
	v_mov_b32_e32 v188, v110
	v_mov_b32_e32 v189, v111
	v_mov_b32_e32 v190, v112
	v_mov_b32_e32 v191, v113
	v_mov_b32_e32 v192, v114
	v_mov_b32_e32 v193, v115
	v_mov_b32_e32 v194, v116
	v_mov_b32_e32 v195, v117
	v_mov_b32_e32 v208, v118
	v_mov_b32_e32 v209, v119
	v_mov_b32_e32 v210, v120
	v_mov_b32_e32 v211, v121
	v_mov_b32_e32 v212, v122
	v_mov_b32_e32 v213, v123
	v_mov_b32_e32 v214, v124
	v_mov_b32_e32 v215, v125
	v_mov_b32_e32 v216, v126
	v_mov_b32_e32 v217, v127
	v_mov_b32_e32 v218, v128
	v_mov_b32_e32 v219, v129
	v_mov_b32_e32 v220, v136
	v_mov_b32_e32 v221, v137
	v_mov_b32_e32 v222, v138
	v_mov_b32_e32 v223, v139
	v_mov_b32_e32 v242, v140
	v_mov_b32_e32 v243, v141
	v_mov_b32_e32 v244, v142
	v_mov_b32_e32 v245, v143
	v_mov_b32_e32 v199, v144
	v_mov_b32_e32 v206, v145
	v_mov_b32_e32 v207, v146
	v_mov_b32_e32 v226, v147
	s_mov_b32 s32, 1
	s_branch .LBB0_222

.Lf2_k:
	s_waitcnt vmcnt(0)
	s_barrier
	s_add_i32 m0, s64, 0xc000
	s_nop 0
	global_load_lds_dwordx4 v76, s[58:59]
	s_add_i32 m0, s64, 0xd000
	s_nop 0
	global_load_lds_dwordx4 v77, s[58:59]
	s_add_i32 m0, s64, 0xe000
	s_nop 0
	global_load_lds_dwordx4 v78, s[58:59]
	s_add_i32 m0, s64, 0xf000
	s_nop 0
	global_load_lds_dwordx4 v79, s[58:59]
	s_add_u32 s58, s58, 0x80
	s_addc_u32 s59, s59, 0
	ds_read_b128 v[148:151], v80 offset:0
	ds_read_b128 v[152:155], v80 offset:2048
	ds_read_b128 v[156:159], v80 offset:4096
	ds_read_b128 v[160:163], v80 offset:6144
	ds_read_b128 v[188:191], v144 offset:32768
	ds_read_b128 v[192:195], v144 offset:34816
	ds_read_b128 v[208:211], v144 offset:36864
	ds_read_b128 v[212:215], v144 offset:38912
	ds_read_b128 v[164:167], v80 offset:16384
	ds_read_b128 v[168:171], v80 offset:18432
	ds_read_b128 v[174:177], v80 offset:20480
	ds_read_b128 v[182:185], v80 offset:22528
	s_setprio 1
	s_waitcnt lgkmcnt(4)
	v_mfma_f32_16x16x32_bf16 v[62:65], v[188:191], v[148:151], v[62:65]
	v_mfma_f32_16x16x32_bf16 v[54:57], v[192:195], v[148:151], v[54:57]
	v_mfma_f32_16x16x32_bf16 v[58:61], v[208:211], v[148:151], v[58:61]
	v_mfma_f32_16x16x32_bf16 v[50:53], v[212:215], v[148:151], v[50:53]
	v_mfma_f32_16x16x32_bf16 v[46:49], v[188:191], v[152:155], v[46:49]
	v_mfma_f32_16x16x32_bf16 v[38:41], v[192:195], v[152:155], v[38:41]
	v_mfma_f32_16x16x32_bf16 v[42:45], v[208:211], v[152:155], v[42:45]
	v_mfma_f32_16x16x32_bf16 v[34:37], v[212:215], v[152:155], v[34:37]
	v_mfma_f32_16x16x32_bf16 v[30:33], v[188:191], v[156:159], v[30:33]
	v_mfma_f32_16x16x32_bf16 v[22:25], v[192:195], v[156:159], v[22:25]
	v_mfma_f32_16x16x32_bf16 v[26:29], v[208:211], v[156:159], v[26:29]
	v_mfma_f32_16x16x32_bf16 v[18:21], v[212:215], v[156:159], v[18:21]
	v_mfma_f32_16x16x32_bf16 v[14:17], v[188:191], v[160:163], v[14:17]
	v_mfma_f32_16x16x32_bf16 v[6:9], v[192:195], v[160:163], v[6:9]
	v_mfma_f32_16x16x32_bf16 v[10:13], v[208:211], v[160:163], v[10:13]
	v_mfma_f32_16x16x32_bf16 v[2:5], v[212:215], v[160:163], v[2:5]
	s_waitcnt lgkmcnt(0)
	v_mfma_f32_16x16x32_bf16 v[66:69], v[188:191], v[164:167], v[66:69]
	v_mfma_f32_16x16x32_bf16 v[70:73], v[192:195], v[164:167], v[70:73]
	v_mfma_f32_16x16x32_bf16 v[82:85], v[208:211], v[164:167], v[82:85]
	v_mfma_f32_16x16x32_bf16 v[86:89], v[212:215], v[164:167], v[86:89]
	v_mfma_f32_16x16x32_bf16 v[90:93], v[188:191], v[168:171], v[90:93]
	v_mfma_f32_16x16x32_bf16 v[94:97], v[192:195], v[168:171], v[94:97]
	v_mfma_f32_16x16x32_bf16 v[98:101], v[208:211], v[168:171], v[98:101]
	v_mfma_f32_16x16x32_bf16 v[102:105], v[212:215], v[168:171], v[102:105]
	v_mfma_f32_16x16x32_bf16 v[106:109], v[188:191], v[174:177], v[106:109]
	v_mfma_f32_16x16x32_bf16 v[110:113], v[192:195], v[174:177], v[110:113]
	v_mfma_f32_16x16x32_bf16 v[114:117], v[208:211], v[174:177], v[114:117]
	v_mfma_f32_16x16x32_bf16 v[118:121], v[212:215], v[174:177], v[118:121]
	v_mfma_f32_16x16x32_bf16 v[122:125], v[188:191], v[182:185], v[122:125]
	v_mfma_f32_16x16x32_bf16 v[126:129], v[192:195], v[182:185], v[126:129]
	v_mfma_f32_16x16x32_bf16 v[136:139], v[208:211], v[182:185], v[136:139]
	v_mfma_f32_16x16x32_bf16 v[140:143], v[212:215], v[182:185], v[140:143]
	s_setprio 0
	ds_read_b128 v[148:151], v81 offset:0
	ds_read_b128 v[152:155], v81 offset:2048
	ds_read_b128 v[156:159], v81 offset:4096
	ds_read_b128 v[160:163], v81 offset:6144
	ds_read_b128 v[188:191], v145 offset:32768
	ds_read_b128 v[192:195], v145 offset:34816
	ds_read_b128 v[208:211], v145 offset:36864
	ds_read_b128 v[212:215], v145 offset:38912
	ds_read_b128 v[164:167], v81 offset:16384
	ds_read_b128 v[168:171], v81 offset:18432
	ds_read_b128 v[174:177], v81 offset:20480
	ds_read_b128 v[182:185], v81 offset:22528
	s_waitcnt lgkmcnt(0)
	s_barrier
	s_add_i32 m0, s64, 0x0
	s_nop 0
	global_load_lds_dwordx4 v76, s[50:51]
	s_add_i32 m0, s64, 0x1000
	s_nop 0
	global_load_lds_dwordx4 v77, s[50:51]
	s_add_i32 m0, s64, 0x2000
	s_nop 0
	global_load_lds_dwordx4 v78, s[50:51]
	s_add_i32 m0, s64, 0x3000
	s_nop 0
	global_load_lds_dwordx4 v79, s[50:51]
	s_add_i32 m0, s64, 0x4000
	s_nop 0
	global_load_lds_dwordx4 v76, s[52:53]
	s_add_i32 m0, s64, 0x5000
	s_nop 0
	global_load_lds_dwordx4 v77, s[52:53]
	s_add_i32 m0, s64, 0x6000
	s_nop 0
	global_load_lds_dwordx4 v78, s[52:53]
	s_add_i32 m0, s64, 0x7000
	s_nop 0
	global_load_lds_dwordx4 v79, s[52:53]
	s_add_u32 s50, s50, 0x80
	s_addc_u32 s51, s51, 0
	s_add_u32 s52, s52, 0x80
	s_addc_u32 s53, s53, 0
	s_setprio 1
	v_mfma_f32_16x16x32_bf16 v[62:65], v[188:191], v[148:151], v[62:65]
	v_mfma_f32_16x16x32_bf16 v[54:57], v[192:195], v[148:151], v[54:57]
	v_mfma_f32_16x16x32_bf16 v[58:61], v[208:211], v[148:151], v[58:61]
	v_mfma_f32_16x16x32_bf16 v[50:53], v[212:215], v[148:151], v[50:53]
	v_mfma_f32_16x16x32_bf16 v[46:49], v[188:191], v[152:155], v[46:49]
	v_mfma_f32_16x16x32_bf16 v[38:41], v[192:195], v[152:155], v[38:41]
	v_mfma_f32_16x16x32_bf16 v[42:45], v[208:211], v[152:155], v[42:45]
	v_mfma_f32_16x16x32_bf16 v[34:37], v[212:215], v[152:155], v[34:37]
	v_mfma_f32_16x16x32_bf16 v[30:33], v[188:191], v[156:159], v[30:33]
	v_mfma_f32_16x16x32_bf16 v[22:25], v[192:195], v[156:159], v[22:25]
	v_mfma_f32_16x16x32_bf16 v[26:29], v[208:211], v[156:159], v[26:29]
	v_mfma_f32_16x16x32_bf16 v[18:21], v[212:215], v[156:159], v[18:21]
	v_mfma_f32_16x16x32_bf16 v[14:17], v[188:191], v[160:163], v[14:17]
	v_mfma_f32_16x16x32_bf16 v[6:9], v[192:195], v[160:163], v[6:9]
	v_mfma_f32_16x16x32_bf16 v[10:13], v[208:211], v[160:163], v[10:13]
	v_mfma_f32_16x16x32_bf16 v[2:5], v[212:215], v[160:163], v[2:5]
	v_mfma_f32_16x16x32_bf16 v[66:69], v[188:191], v[164:167], v[66:69]
	v_mfma_f32_16x16x32_bf16 v[70:73], v[192:195], v[164:167], v[70:73]
	v_mfma_f32_16x16x32_bf16 v[82:85], v[208:211], v[164:167], v[82:85]
	v_mfma_f32_16x16x32_bf16 v[86:89], v[212:215], v[164:167], v[86:89]
	v_mfma_f32_16x16x32_bf16 v[90:93], v[188:191], v[168:171], v[90:93]
	v_mfma_f32_16x16x32_bf16 v[94:97], v[192:195], v[168:171], v[94:97]
	v_mfma_f32_16x16x32_bf16 v[98:101], v[208:211], v[168:171], v[98:101]
	v_mfma_f32_16x16x32_bf16 v[102:105], v[212:215], v[168:171], v[102:105]
	v_mfma_f32_16x16x32_bf16 v[106:109], v[188:191], v[174:177], v[106:109]
	v_mfma_f32_16x16x32_bf16 v[110:113], v[192:195], v[174:177], v[110:113]
	v_mfma_f32_16x16x32_bf16 v[114:117], v[208:211], v[174:177], v[114:117]
	v_mfma_f32_16x16x32_bf16 v[118:121], v[212:215], v[174:177], v[118:121]
	v_mfma_f32_16x16x32_bf16 v[122:125], v[188:191], v[182:185], v[122:125]
	v_mfma_f32_16x16x32_bf16 v[126:129], v[192:195], v[182:185], v[126:129]
	v_mfma_f32_16x16x32_bf16 v[136:139], v[208:211], v[182:185], v[136:139]
	v_mfma_f32_16x16x32_bf16 v[140:143], v[212:215], v[182:185], v[140:143]
	s_setprio 0
	s_waitcnt vmcnt(0)
	s_barrier
	s_add_i32 m0, s64, 0x8000
	s_nop 0
	global_load_lds_dwordx4 v76, s[58:59]
	s_add_i32 m0, s64, 0x9000
	s_nop 0
	global_load_lds_dwordx4 v77, s[58:59]
	s_add_i32 m0, s64, 0xa000
	s_nop 0
	global_load_lds_dwordx4 v78, s[58:59]
	s_add_i32 m0, s64, 0xb000
	s_nop 0
	global_load_lds_dwordx4 v79, s[58:59]
	s_add_u32 s58, s58, 0x80
	s_addc_u32 s59, s59, 0
	ds_read_b128 v[148:151], v80 offset:0
	ds_read_b128 v[152:155], v80 offset:2048
	ds_read_b128 v[156:159], v80 offset:4096
	ds_read_b128 v[160:163], v80 offset:6144
	ds_read_b128 v[188:191], v144 offset:49152
	ds_read_b128 v[192:195], v144 offset:51200
	ds_read_b128 v[208:211], v144 offset:53248
	ds_read_b128 v[212:215], v144 offset:55296
	ds_read_b128 v[164:167], v80 offset:16384
	ds_read_b128 v[168:171], v80 offset:18432
	ds_read_b128 v[174:177], v80 offset:20480
	ds_read_b128 v[182:185], v80 offset:22528
	s_setprio 1
	s_waitcnt lgkmcnt(4)
	v_mfma_f32_16x16x32_bf16 v[62:65], v[188:191], v[148:151], v[62:65]
	v_mfma_f32_16x16x32_bf16 v[54:57], v[192:195], v[148:151], v[54:57]
	v_mfma_f32_16x16x32_bf16 v[58:61], v[208:211], v[148:151], v[58:61]
	v_mfma_f32_16x16x32_bf16 v[50:53], v[212:215], v[148:151], v[50:53]
	v_mfma_f32_16x16x32_bf16 v[46:49], v[188:191], v[152:155], v[46:49]
	v_mfma_f32_16x16x32_bf16 v[38:41], v[192:195], v[152:155], v[38:41]
	v_mfma_f32_16x16x32_bf16 v[42:45], v[208:211], v[152:155], v[42:45]
	v_mfma_f32_16x16x32_bf16 v[34:37], v[212:215], v[152:155], v[34:37]
	v_mfma_f32_16x16x32_bf16 v[30:33], v[188:191], v[156:159], v[30:33]
	v_mfma_f32_16x16x32_bf16 v[22:25], v[192:195], v[156:159], v[22:25]
	v_mfma_f32_16x16x32_bf16 v[26:29], v[208:211], v[156:159], v[26:29]
	v_mfma_f32_16x16x32_bf16 v[18:21], v[212:215], v[156:159], v[18:21]
	v_mfma_f32_16x16x32_bf16 v[14:17], v[188:191], v[160:163], v[14:17]
	v_mfma_f32_16x16x32_bf16 v[6:9], v[192:195], v[160:163], v[6:9]
	v_mfma_f32_16x16x32_bf16 v[10:13], v[208:211], v[160:163], v[10:13]
	v_mfma_f32_16x16x32_bf16 v[2:5], v[212:215], v[160:163], v[2:5]
	s_waitcnt lgkmcnt(0)
	v_mfma_f32_16x16x32_bf16 v[66:69], v[188:191], v[164:167], v[66:69]
	v_mfma_f32_16x16x32_bf16 v[70:73], v[192:195], v[164:167], v[70:73]
	v_mfma_f32_16x16x32_bf16 v[82:85], v[208:211], v[164:167], v[82:85]
	v_mfma_f32_16x16x32_bf16 v[86:89], v[212:215], v[164:167], v[86:89]
	v_mfma_f32_16x16x32_bf16 v[90:93], v[188:191], v[168:171], v[90:93]
	v_mfma_f32_16x16x32_bf16 v[94:97], v[192:195], v[168:171], v[94:97]
	v_mfma_f32_16x16x32_bf16 v[98:101], v[208:211], v[168:171], v[98:101]
	v_mfma_f32_16x16x32_bf16 v[102:105], v[212:215], v[168:171], v[102:105]
	v_mfma_f32_16x16x32_bf16 v[106:109], v[188:191], v[174:177], v[106:109]
	v_mfma_f32_16x16x32_bf16 v[110:113], v[192:195], v[174:177], v[110:113]
	v_mfma_f32_16x16x32_bf16 v[114:117], v[208:211], v[174:177], v[114:117]
	v_mfma_f32_16x16x32_bf16 v[118:121], v[212:215], v[174:177], v[118:121]
	v_mfma_f32_16x16x32_bf16 v[122:125], v[188:191], v[182:185], v[122:125]
	v_mfma_f32_16x16x32_bf16 v[126:129], v[192:195], v[182:185], v[126:129]
	v_mfma_f32_16x16x32_bf16 v[136:139], v[208:211], v[182:185], v[136:139]
	v_mfma_f32_16x16x32_bf16 v[140:143], v[212:215], v[182:185], v[140:143]
	s_setprio 0
	ds_read_b128 v[148:151], v81 offset:0
	ds_read_b128 v[152:155], v81 offset:2048
	ds_read_b128 v[156:159], v81 offset:4096
	ds_read_b128 v[160:163], v81 offset:6144
	ds_read_b128 v[188:191], v145 offset:49152
	ds_read_b128 v[192:195], v145 offset:51200
	ds_read_b128 v[208:211], v145 offset:53248
	ds_read_b128 v[212:215], v145 offset:55296
	ds_read_b128 v[164:167], v81 offset:16384
	ds_read_b128 v[168:171], v81 offset:18432
	ds_read_b128 v[174:177], v81 offset:20480
	ds_read_b128 v[182:185], v81 offset:22528
	s_waitcnt lgkmcnt(0)
	s_barrier
	s_add_i32 m0, s64, 0x0
	s_nop 0
	global_load_lds_dwordx4 v76, s[50:51]
	s_add_i32 m0, s64, 0x1000
	s_nop 0
	global_load_lds_dwordx4 v77, s[50:51]
	s_add_i32 m0, s64, 0x2000
	s_nop 0
	global_load_lds_dwordx4 v78, s[50:51]
	s_add_i32 m0, s64, 0x3000
	s_nop 0
	global_load_lds_dwordx4 v79, s[50:51]
	s_add_i32 m0, s64, 0x4000
	s_nop 0
	global_load_lds_dwordx4 v76, s[52:53]
	s_add_i32 m0, s64, 0x5000
	s_nop 0
	global_load_lds_dwordx4 v77, s[52:53]
	s_add_i32 m0, s64, 0x6000
	s_nop 0
	global_load_lds_dwordx4 v78, s[52:53]
	s_add_i32 m0, s64, 0x7000
	s_nop 0
	global_load_lds_dwordx4 v79, s[52:53]
	s_add_u32 s50, s50, 0x80
	s_addc_u32 s51, s51, 0
	s_add_u32 s52, s52, 0x80
	s_addc_u32 s53, s53, 0
	s_setprio 1
	v_mfma_f32_16x16x32_bf16 v[62:65], v[188:191], v[148:151], v[62:65]
	v_mfma_f32_16x16x32_bf16 v[54:57], v[192:195], v[148:151], v[54:57]
	v_mfma_f32_16x16x32_bf16 v[58:61], v[208:211], v[148:151], v[58:61]
	v_mfma_f32_16x16x32_bf16 v[50:53], v[212:215], v[148:151], v[50:53]
	v_mfma_f32_16x16x32_bf16 v[46:49], v[188:191], v[152:155], v[46:49]
	v_mfma_f32_16x16x32_bf16 v[38:41], v[192:195], v[152:155], v[38:41]
	v_mfma_f32_16x16x32_bf16 v[42:45], v[208:211], v[152:155], v[42:45]
	v_mfma_f32_16x16x32_bf16 v[34:37], v[212:215], v[152:155], v[34:37]
	v_mfma_f32_16x16x32_bf16 v[30:33], v[188:191], v[156:159], v[30:33]
	v_mfma_f32_16x16x32_bf16 v[22:25], v[192:195], v[156:159], v[22:25]
	v_mfma_f32_16x16x32_bf16 v[26:29], v[208:211], v[156:159], v[26:29]
	v_mfma_f32_16x16x32_bf16 v[18:21], v[212:215], v[156:159], v[18:21]
	v_mfma_f32_16x16x32_bf16 v[14:17], v[188:191], v[160:163], v[14:17]
	v_mfma_f32_16x16x32_bf16 v[6:9], v[192:195], v[160:163], v[6:9]
	v_mfma_f32_16x16x32_bf16 v[10:13], v[208:211], v[160:163], v[10:13]
	v_mfma_f32_16x16x32_bf16 v[2:5], v[212:215], v[160:163], v[2:5]
	v_mfma_f32_16x16x32_bf16 v[66:69], v[188:191], v[164:167], v[66:69]
	v_mfma_f32_16x16x32_bf16 v[70:73], v[192:195], v[164:167], v[70:73]
	v_mfma_f32_16x16x32_bf16 v[82:85], v[208:211], v[164:167], v[82:85]
	v_mfma_f32_16x16x32_bf16 v[86:89], v[212:215], v[164:167], v[86:89]
	v_mfma_f32_16x16x32_bf16 v[90:93], v[188:191], v[168:171], v[90:93]
	v_mfma_f32_16x16x32_bf16 v[94:97], v[192:195], v[168:171], v[94:97]
	v_mfma_f32_16x16x32_bf16 v[98:101], v[208:211], v[168:171], v[98:101]
	v_mfma_f32_16x16x32_bf16 v[102:105], v[212:215], v[168:171], v[102:105]
	v_mfma_f32_16x16x32_bf16 v[106:109], v[188:191], v[174:177], v[106:109]
	v_mfma_f32_16x16x32_bf16 v[110:113], v[192:195], v[174:177], v[110:113]
	v_mfma_f32_16x16x32_bf16 v[114:117], v[208:211], v[174:177], v[114:117]
	v_mfma_f32_16x16x32_bf16 v[118:121], v[212:215], v[174:177], v[118:121]
	v_mfma_f32_16x16x32_bf16 v[122:125], v[188:191], v[182:185], v[122:125]
	v_mfma_f32_16x16x32_bf16 v[126:129], v[192:195], v[182:185], v[126:129]
	v_mfma_f32_16x16x32_bf16 v[136:139], v[208:211], v[182:185], v[136:139]
	v_mfma_f32_16x16x32_bf16 v[140:143], v[212:215], v[182:185], v[140:143]
	s_setprio 0
	s_add_i32 s65, s65, -1
	s_cmp_lg_u32 s65, 0
	s_cbranch_scc1 .Lf2_k
	s_waitcnt vmcnt(0)
	s_barrier
	s_add_i32 m0, s64, 0xc000
	s_nop 0
	global_load_lds_dwordx4 v76, s[58:59]
	s_add_i32 m0, s64, 0xd000
	s_nop 0
	global_load_lds_dwordx4 v77, s[58:59]
	s_add_i32 m0, s64, 0xe000
	s_nop 0
	global_load_lds_dwordx4 v78, s[58:59]
	s_add_i32 m0, s64, 0xf000
	s_nop 0
	global_load_lds_dwordx4 v79, s[58:59]
	s_add_u32 s58, s58, 0x80
	s_addc_u32 s59, s59, 0
	ds_read_b128 v[148:151], v80 offset:0
	ds_read_b128 v[152:155], v80 offset:2048
	ds_read_b128 v[156:159], v80 offset:4096
	ds_read_b128 v[160:163], v80 offset:6144
	ds_read_b128 v[188:191], v144 offset:32768
	ds_read_b128 v[192:195], v144 offset:34816
	ds_read_b128 v[208:211], v144 offset:36864
	ds_read_b128 v[212:215], v144 offset:38912
	ds_read_b128 v[164:167], v80 offset:16384
	ds_read_b128 v[168:171], v80 offset:18432
	ds_read_b128 v[174:177], v80 offset:20480
	ds_read_b128 v[182:185], v80 offset:22528
	s_setprio 1
	s_waitcnt lgkmcnt(4)
	v_mfma_f32_16x16x32_bf16 v[62:65], v[188:191], v[148:151], v[62:65]
	v_mfma_f32_16x16x32_bf16 v[54:57], v[192:195], v[148:151], v[54:57]
	v_mfma_f32_16x16x32_bf16 v[58:61], v[208:211], v[148:151], v[58:61]
	v_mfma_f32_16x16x32_bf16 v[50:53], v[212:215], v[148:151], v[50:53]
	v_mfma_f32_16x16x32_bf16 v[46:49], v[188:191], v[152:155], v[46:49]
	v_mfma_f32_16x16x32_bf16 v[38:41], v[192:195], v[152:155], v[38:41]
	v_mfma_f32_16x16x32_bf16 v[42:45], v[208:211], v[152:155], v[42:45]
	v_mfma_f32_16x16x32_bf16 v[34:37], v[212:215], v[152:155], v[34:37]
	v_mfma_f32_16x16x32_bf16 v[30:33], v[188:191], v[156:159], v[30:33]
	v_mfma_f32_16x16x32_bf16 v[22:25], v[192:195], v[156:159], v[22:25]
	v_mfma_f32_16x16x32_bf16 v[26:29], v[208:211], v[156:159], v[26:29]
	v_mfma_f32_16x16x32_bf16 v[18:21], v[212:215], v[156:159], v[18:21]
	v_mfma_f32_16x16x32_bf16 v[14:17], v[188:191], v[160:163], v[14:17]
	v_mfma_f32_16x16x32_bf16 v[6:9], v[192:195], v[160:163], v[6:9]
	v_mfma_f32_16x16x32_bf16 v[10:13], v[208:211], v[160:163], v[10:13]
	v_mfma_f32_16x16x32_bf16 v[2:5], v[212:215], v[160:163], v[2:5]
	s_waitcnt lgkmcnt(0)
	v_mfma_f32_16x16x32_bf16 v[66:69], v[188:191], v[164:167], v[66:69]
	v_mfma_f32_16x16x32_bf16 v[70:73], v[192:195], v[164:167], v[70:73]
	v_mfma_f32_16x16x32_bf16 v[82:85], v[208:211], v[164:167], v[82:85]
	v_mfma_f32_16x16x32_bf16 v[86:89], v[212:215], v[164:167], v[86:89]
	v_mfma_f32_16x16x32_bf16 v[90:93], v[188:191], v[168:171], v[90:93]
	v_mfma_f32_16x16x32_bf16 v[94:97], v[192:195], v[168:171], v[94:97]
	v_mfma_f32_16x16x32_bf16 v[98:101], v[208:211], v[168:171], v[98:101]
	v_mfma_f32_16x16x32_bf16 v[102:105], v[212:215], v[168:171], v[102:105]
	v_mfma_f32_16x16x32_bf16 v[106:109], v[188:191], v[174:177], v[106:109]
	v_mfma_f32_16x16x32_bf16 v[110:113], v[192:195], v[174:177], v[110:113]
	v_mfma_f32_16x16x32_bf16 v[114:117], v[208:211], v[174:177], v[114:117]
	v_mfma_f32_16x16x32_bf16 v[118:121], v[212:215], v[174:177], v[118:121]
	v_mfma_f32_16x16x32_bf16 v[122:125], v[188:191], v[182:185], v[122:125]
	v_mfma_f32_16x16x32_bf16 v[126:129], v[192:195], v[182:185], v[126:129]
	v_mfma_f32_16x16x32_bf16 v[136:139], v[208:211], v[182:185], v[136:139]
	v_mfma_f32_16x16x32_bf16 v[140:143], v[212:215], v[182:185], v[140:143]
	s_setprio 0
	ds_read_b128 v[148:151], v81 offset:0
	ds_read_b128 v[152:155], v81 offset:2048
	ds_read_b128 v[156:159], v81 offset:4096
	ds_read_b128 v[160:163], v81 offset:6144
	ds_read_b128 v[188:191], v145 offset:32768
	ds_read_b128 v[192:195], v145 offset:34816
	ds_read_b128 v[208:211], v145 offset:36864
	ds_read_b128 v[212:215], v145 offset:38912
	ds_read_b128 v[164:167], v81 offset:16384
	ds_read_b128 v[168:171], v81 offset:18432
	ds_read_b128 v[174:177], v81 offset:20480
	ds_read_b128 v[182:185], v81 offset:22528
	s_waitcnt lgkmcnt(0)
	s_barrier
	s_add_i32 m0, s64, 0x0
	s_nop 0
	global_load_lds_dwordx4 v76, s[50:51]
	s_add_i32 m0, s64, 0x1000
	s_nop 0
	global_load_lds_dwordx4 v77, s[50:51]
	s_add_i32 m0, s64, 0x2000
	s_nop 0
	global_load_lds_dwordx4 v78, s[50:51]
	s_add_i32 m0, s64, 0x3000
	s_nop 0
	global_load_lds_dwordx4 v79, s[50:51]
	s_add_i32 m0, s64, 0x4000
	s_nop 0
	global_load_lds_dwordx4 v76, s[52:53]
	s_add_i32 m0, s64, 0x5000
	s_nop 0
	global_load_lds_dwordx4 v77, s[52:53]
	s_add_i32 m0, s64, 0x6000
	s_nop 0
	global_load_lds_dwordx4 v78, s[52:53]
	s_add_i32 m0, s64, 0x7000
	s_nop 0
	global_load_lds_dwordx4 v79, s[52:53]
	s_add_u32 s50, s50, 0x80
	s_addc_u32 s51, s51, 0
	s_add_u32 s52, s52, 0x80
	s_addc_u32 s53, s53, 0
	s_setprio 1
	v_mfma_f32_16x16x32_bf16 v[62:65], v[188:191], v[148:151], v[62:65]
	v_mfma_f32_16x16x32_bf16 v[54:57], v[192:195], v[148:151], v[54:57]
	v_mfma_f32_16x16x32_bf16 v[58:61], v[208:211], v[148:151], v[58:61]
	v_mfma_f32_16x16x32_bf16 v[50:53], v[212:215], v[148:151], v[50:53]
	v_mfma_f32_16x16x32_bf16 v[46:49], v[188:191], v[152:155], v[46:49]
	v_mfma_f32_16x16x32_bf16 v[38:41], v[192:195], v[152:155], v[38:41]
	v_mfma_f32_16x16x32_bf16 v[42:45], v[208:211], v[152:155], v[42:45]
	v_mfma_f32_16x16x32_bf16 v[34:37], v[212:215], v[152:155], v[34:37]
	v_mfma_f32_16x16x32_bf16 v[30:33], v[188:191], v[156:159], v[30:33]
	v_mfma_f32_16x16x32_bf16 v[22:25], v[192:195], v[156:159], v[22:25]
	v_mfma_f32_16x16x32_bf16 v[26:29], v[208:211], v[156:159], v[26:29]
	v_mfma_f32_16x16x32_bf16 v[18:21], v[212:215], v[156:159], v[18:21]
	v_mfma_f32_16x16x32_bf16 v[14:17], v[188:191], v[160:163], v[14:17]
	v_mfma_f32_16x16x32_bf16 v[6:9], v[192:195], v[160:163], v[6:9]
	v_mfma_f32_16x16x32_bf16 v[10:13], v[208:211], v[160:163], v[10:13]
	v_mfma_f32_16x16x32_bf16 v[2:5], v[212:215], v[160:163], v[2:5]
	v_mfma_f32_16x16x32_bf16 v[66:69], v[188:191], v[164:167], v[66:69]
	v_mfma_f32_16x16x32_bf16 v[70:73], v[192:195], v[164:167], v[70:73]
	v_mfma_f32_16x16x32_bf16 v[82:85], v[208:211], v[164:167], v[82:85]
	v_mfma_f32_16x16x32_bf16 v[86:89], v[212:215], v[164:167], v[86:89]
	v_mfma_f32_16x16x32_bf16 v[90:93], v[188:191], v[168:171], v[90:93]
	v_mfma_f32_16x16x32_bf16 v[94:97], v[192:195], v[168:171], v[94:97]
	v_mfma_f32_16x16x32_bf16 v[98:101], v[208:211], v[168:171], v[98:101]
	v_mfma_f32_16x16x32_bf16 v[102:105], v[212:215], v[168:171], v[102:105]
	v_mfma_f32_16x16x32_bf16 v[106:109], v[188:191], v[174:177], v[106:109]
	v_mfma_f32_16x16x32_bf16 v[110:113], v[192:195], v[174:177], v[110:113]
	v_mfma_f32_16x16x32_bf16 v[114:117], v[208:211], v[174:177], v[114:117]
	v_mfma_f32_16x16x32_bf16 v[118:121], v[212:215], v[174:177], v[118:121]
	v_mfma_f32_16x16x32_bf16 v[122:125], v[188:191], v[182:185], v[122:125]
	v_mfma_f32_16x16x32_bf16 v[126:129], v[192:195], v[182:185], v[126:129]
	v_mfma_f32_16x16x32_bf16 v[136:139], v[208:211], v[182:185], v[136:139]
	v_mfma_f32_16x16x32_bf16 v[140:143], v[212:215], v[182:185], v[140:143]
	s_setprio 0
	s_waitcnt vmcnt(0)
	s_barrier
	ds_read_b128 v[148:151], v80 offset:0
	ds_read_b128 v[152:155], v80 offset:2048
	ds_read_b128 v[156:159], v80 offset:4096
	ds_read_b128 v[160:163], v80 offset:6144
	ds_read_b128 v[188:191], v144 offset:49152
	ds_read_b128 v[192:195], v144 offset:51200
	ds_read_b128 v[208:211], v144 offset:53248
	ds_read_b128 v[212:215], v144 offset:55296
	ds_read_b128 v[164:167], v80 offset:16384
	ds_read_b128 v[168:171], v80 offset:18432
	ds_read_b128 v[174:177], v80 offset:20480
	ds_read_b128 v[182:185], v80 offset:22528
	s_setprio 1
	s_waitcnt lgkmcnt(4)
	v_mfma_f32_16x16x32_bf16 v[62:65], v[188:191], v[148:151], v[62:65]
	v_mfma_f32_16x16x32_bf16 v[54:57], v[192:195], v[148:151], v[54:57]
	v_mfma_f32_16x16x32_bf16 v[58:61], v[208:211], v[148:151], v[58:61]
	v_mfma_f32_16x16x32_bf16 v[50:53], v[212:215], v[148:151], v[50:53]
	v_mfma_f32_16x16x32_bf16 v[46:49], v[188:191], v[152:155], v[46:49]
	v_mfma_f32_16x16x32_bf16 v[38:41], v[192:195], v[152:155], v[38:41]
	v_mfma_f32_16x16x32_bf16 v[42:45], v[208:211], v[152:155], v[42:45]
	v_mfma_f32_16x16x32_bf16 v[34:37], v[212:215], v[152:155], v[34:37]
	v_mfma_f32_16x16x32_bf16 v[30:33], v[188:191], v[156:159], v[30:33]
	v_mfma_f32_16x16x32_bf16 v[22:25], v[192:195], v[156:159], v[22:25]
	v_mfma_f32_16x16x32_bf16 v[26:29], v[208:211], v[156:159], v[26:29]
	v_mfma_f32_16x16x32_bf16 v[18:21], v[212:215], v[156:159], v[18:21]
	v_mfma_f32_16x16x32_bf16 v[14:17], v[188:191], v[160:163], v[14:17]
	v_mfma_f32_16x16x32_bf16 v[6:9], v[192:195], v[160:163], v[6:9]
	v_mfma_f32_16x16x32_bf16 v[10:13], v[208:211], v[160:163], v[10:13]
	v_mfma_f32_16x16x32_bf16 v[2:5], v[212:215], v[160:163], v[2:5]
	s_waitcnt lgkmcnt(0)
	v_mfma_f32_16x16x32_bf16 v[66:69], v[188:191], v[164:167], v[66:69]
	v_mfma_f32_16x16x32_bf16 v[70:73], v[192:195], v[164:167], v[70:73]
	v_mfma_f32_16x16x32_bf16 v[82:85], v[208:211], v[164:167], v[82:85]
	v_mfma_f32_16x16x32_bf16 v[86:89], v[212:215], v[164:167], v[86:89]
	v_mfma_f32_16x16x32_bf16 v[90:93], v[188:191], v[168:171], v[90:93]
	v_mfma_f32_16x16x32_bf16 v[94:97], v[192:195], v[168:171], v[94:97]
	v_mfma_f32_16x16x32_bf16 v[98:101], v[208:211], v[168:171], v[98:101]
	v_mfma_f32_16x16x32_bf16 v[102:105], v[212:215], v[168:171], v[102:105]
	v_mfma_f32_16x16x32_bf16 v[106:109], v[188:191], v[174:177], v[106:109]
	v_mfma_f32_16x16x32_bf16 v[110:113], v[192:195], v[174:177], v[110:113]
	v_mfma_f32_16x16x32_bf16 v[114:117], v[208:211], v[174:177], v[114:117]
	v_mfma_f32_16x16x32_bf16 v[118:121], v[212:215], v[174:177], v[118:121]
	v_mfma_f32_16x16x32_bf16 v[122:125], v[188:191], v[182:185], v[122:125]
	v_mfma_f32_16x16x32_bf16 v[126:129], v[192:195], v[182:185], v[126:129]
	v_mfma_f32_16x16x32_bf16 v[136:139], v[208:211], v[182:185], v[136:139]
	v_mfma_f32_16x16x32_bf16 v[140:143], v[212:215], v[182:185], v[140:143]
	s_setprio 0
	ds_read_b128 v[148:151], v81 offset:0
	ds_read_b128 v[152:155], v81 offset:2048
	ds_read_b128 v[156:159], v81 offset:4096
	ds_read_b128 v[160:163], v81 offset:6144
	ds_read_b128 v[188:191], v145 offset:49152
	ds_read_b128 v[192:195], v145 offset:51200
	ds_read_b128 v[208:211], v145 offset:53248
	ds_read_b128 v[212:215], v145 offset:55296
	ds_read_b128 v[164:167], v81 offset:16384
	ds_read_b128 v[168:171], v81 offset:18432
	ds_read_b128 v[174:177], v81 offset:20480
	ds_read_b128 v[182:185], v81 offset:22528
	s_setprio 1
	s_waitcnt lgkmcnt(4)
	v_mfma_f32_16x16x32_bf16 v[62:65], v[188:191], v[148:151], v[62:65]
	v_mfma_f32_16x16x32_bf16 v[54:57], v[192:195], v[148:151], v[54:57]
	v_mfma_f32_16x16x32_bf16 v[58:61], v[208:211], v[148:151], v[58:61]
	v_mfma_f32_16x16x32_bf16 v[50:53], v[212:215], v[148:151], v[50:53]
	v_mfma_f32_16x16x32_bf16 v[46:49], v[188:191], v[152:155], v[46:49]
	v_mfma_f32_16x16x32_bf16 v[38:41], v[192:195], v[152:155], v[38:41]
	v_mfma_f32_16x16x32_bf16 v[42:45], v[208:211], v[152:155], v[42:45]
	v_mfma_f32_16x16x32_bf16 v[34:37], v[212:215], v[152:155], v[34:37]
	v_mfma_f32_16x16x32_bf16 v[30:33], v[188:191], v[156:159], v[30:33]
	v_mfma_f32_16x16x32_bf16 v[22:25], v[192:195], v[156:159], v[22:25]
	v_mfma_f32_16x16x32_bf16 v[26:29], v[208:211], v[156:159], v[26:29]
	v_mfma_f32_16x16x32_bf16 v[18:21], v[212:215], v[156:159], v[18:21]
	v_mfma_f32_16x16x32_bf16 v[14:17], v[188:191], v[160:163], v[14:17]
	v_mfma_f32_16x16x32_bf16 v[6:9], v[192:195], v[160:163], v[6:9]
	v_mfma_f32_16x16x32_bf16 v[10:13], v[208:211], v[160:163], v[10:13]
	v_mfma_f32_16x16x32_bf16 v[2:5], v[212:215], v[160:163], v[2:5]
	s_waitcnt lgkmcnt(0)
	v_mfma_f32_16x16x32_bf16 v[66:69], v[188:191], v[164:167], v[66:69]
	v_mfma_f32_16x16x32_bf16 v[70:73], v[192:195], v[164:167], v[70:73]
	v_mfma_f32_16x16x32_bf16 v[82:85], v[208:211], v[164:167], v[82:85]
	v_mfma_f32_16x16x32_bf16 v[86:89], v[212:215], v[164:167], v[86:89]
	v_mfma_f32_16x16x32_bf16 v[90:93], v[188:191], v[168:171], v[90:93]
	v_mfma_f32_16x16x32_bf16 v[94:97], v[192:195], v[168:171], v[94:97]
	v_mfma_f32_16x16x32_bf16 v[98:101], v[208:211], v[168:171], v[98:101]
	v_mfma_f32_16x16x32_bf16 v[102:105], v[212:215], v[168:171], v[102:105]
	v_mfma_f32_16x16x32_bf16 v[106:109], v[188:191], v[174:177], v[106:109]
	v_mfma_f32_16x16x32_bf16 v[110:113], v[192:195], v[174:177], v[110:113]
	v_mfma_f32_16x16x32_bf16 v[114:117], v[208:211], v[174:177], v[114:117]
	v_mfma_f32_16x16x32_bf16 v[118:121], v[212:215], v[174:177], v[118:121]
	v_mfma_f32_16x16x32_bf16 v[122:125], v[188:191], v[182:185], v[122:125]
	v_mfma_f32_16x16x32_bf16 v[126:129], v[192:195], v[182:185], v[126:129]
	v_mfma_f32_16x16x32_bf16 v[136:139], v[208:211], v[182:185], v[136:139]
	v_mfma_f32_16x16x32_bf16 v[140:143], v[212:215], v[182:185], v[140:143]
	s_setprio 0
	s_nop 7
	s_nop 7
	s_nop 7
	v_mov_b32_e32 v148, v66
	v_mov_b32_e32 v149, v67
	v_mov_b32_e32 v150, v68
	v_mov_b32_e32 v151, v69
	v_mov_b32_e32 v152, v70
	v_mov_b32_e32 v153, v71
	v_mov_b32_e32 v154, v72
	v_mov_b32_e32 v155, v73
	v_mov_b32_e32 v156, v82
	v_mov_b32_e32 v157, v83
	v_mov_b32_e32 v158, v84
	v_mov_b32_e32 v159, v85
	v_mov_b32_e32 v160, v86
	v_mov_b32_e32 v161, v87
	v_mov_b32_e32 v162, v88
	v_mov_b32_e32 v163, v89
	v_mov_b32_e32 v164, v90
	v_mov_b32_e32 v165, v91
	v_mov_b32_e32 v166, v92
	v_mov_b32_e32 v167, v93
	v_mov_b32_e32 v168, v94
	v_mov_b32_e32 v169, v95
	v_mov_b32_e32 v170, v96
	v_mov_b32_e32 v171, v97
	v_mov_b32_e32 v174, v98
	v_mov_b32_e32 v175, v99
	v_mov_b32_e32 v176, v100
	v_mov_b32_e32 v177, v101
	v_mov_b32_e32 v182, v102
	v_mov_b32_e32 v183, v103
	v_mov_b32_e32 v184, v104
	v_mov_b32_e32 v185, v105
	v_mov_b32_e32 v188, v106
	v_mov_b32_e32 v189, v107
	v_mov_b32_e32 v190, v108
	v_mov_b32_e32 v191, v109
	v_mov_b32_e32 v192, v110
	v_mov_b32_e32 v193, v111
	v_mov_b32_e32 v194, v112
	v_mov_b32_e32 v195, v113
	v_mov_b32_e32 v208, v114
	v_mov_b32_e32 v209, v115
	v_mov_b32_e32 v210, v116
	v_mov_b32_e32 v211, v117
	v_mov_b32_e32 v212, v118
	v_mov_b32_e32 v213, v119
	v_mov_b32_e32 v214, v120
	v_mov_b32_e32 v215, v121
	v_mov_b32_e32 v216, v122
	v_mov_b32_e32 v217, v123
	v_mov_b32_e32 v218, v124
	v_mov_b32_e32 v219, v125
	v_mov_b32_e32 v220, v126
	v_mov_b32_e32 v221, v127
	v_mov_b32_e32 v222, v128
	v_mov_b32_e32 v223, v129
	v_mov_b32_e32 v242, v136
	v_mov_b32_e32 v243, v137
	v_mov_b32_e32 v244, v138
	v_mov_b32_e32 v245, v139
	v_mov_b32_e32 v199, v140
	v_mov_b32_e32 v206, v141
	v_mov_b32_e32 v207, v142
	v_mov_b32_e32 v226, v143
	s_mov_b32 s32, 1
	s_branch .LBB0_2353
